# recurrence prompt units: static s_setprio 1 for waves 0-3 (on top of the attention older-half raise)
# speedup vs baseline: 1.0088x; 1.0049x over previous
.LBB0_1558:
	v_readlane_b32 s100, v255, 8
	s_cmp_lt_u32 s100, 4
	s_cbranch_scc0 .Lrec_noprio_a
	s_setprio 1
